# out-proj epilogue: accumulators lane-transposed once by ds_bpermute; residual loads and output stores lane-coalesced (4 neighbouring lanes per row)
# speedup vs baseline: 1.0085x; 1.0085x over previous
; #define PG8_STAGE(bufoff, gbase, voff) do { _Pragma("unroll") for (int _i = 0; _i < 2; ++_i) \
;         __builtin_amdgcn_global_load_lds((const unsigned*)((const char*)(gbase) + (voff)[_i]), (LAS unsigned*)(lds + (bufoff) + ldsw + _i * 8192), 16, 0, 0); } while (0)
; #define PG8_LDA(dst, b, h) do { _Pragma("unroll") for (int m = 0; m < 4; ++m) _Pragma("unroll") for (int k = 0; k < 2; ++k) dst[m][k] = *(const LAS bf16x8*)(lds + PG8_SA(b, h) + aoff + m * 2048 + k * 1024); } while (0)
; #define PG8_WAIT_V(n) asm volatile("s_waitcnt vmcnt(" #n ")" ::: "memory")
; #define PG8_WAIT_L(n) asm volatile("s_waitcnt lgkmcnt(" #n ")" ::: "memory")
; template <class Epi, class Sched>
; __device__ __forceinline__ void gemm_phase(LAS unsigned char* lds, const Gemm g, const Sched& S, const Epi& E) {
;     ...
;         for (int t = 0; t < nt; t += 2) {
;             const bool last = (t == nt - 2);
;             const char* a1 = cA + (size_t)(t + 1) * kstep;
;             const char* a2 = last ? nA : cA + (size_t)(t + 2) * kstep; const char* b2 = last ? nB : cB + (size_t)(t + 2) * kstep;
;             const char* a3 = a2 + kstep; const char* b3 = b2 + kstep;
;             PG8_LDB(B0, 0, 0); PG8_SCHED; PG8_LDA(At, 0, 0); PG8_STAGE(PG8_SA(1, 1), a1 + hstep, voffA);
;             PG8_WAIT_L(8); PG8_BAR; PG8_WAIT_L(0); PG8_MMA(0, 0, At, B0); PG8_BAR; PG8_SCHED;
;             PG8_LDB(B1, 0, 1); PG8_STAGE(PG8_SB(0, 0), b2, voffB);
;             PG8_BAR; PG8_WAIT_L(0); PG8_MMA(0, 1, At, B1); PG8_BAR;
;             PG8_LDA(At, 0, 1); PG8_STAGE(PG8_SA(0, 0), a2, voffA);
;             PG8_BAR; PG8_WAIT_L(0); PG8_MMA(1, 0, At, B0); PG8_BAR; PG8_SCHED;
;             PG8_STAGE(PG8_SB(0, 1), b2 + hstep, voffB);
;             PG8_WAIT_V(6); PG8_BAR; PG8_MMA(1, 1, At, B1); PG8_BAR;
;             PG8_LDB(B0, 1, 0); PG8_SCHED; PG8_LDA(At, 1, 0); PG8_STAGE(PG8_SA(0, 1), a2 + hstep, voffA);
;             PG8_WAIT_L(8); PG8_BAR; PG8_WAIT_L(0); PG8_MMA(0, 0, At, B0); PG8_BAR; PG8_SCHED;
;             PG8_LDB(B1, 1, 1); PG8_STAGE(PG8_SB(1, 0), b3, voffB);
;             PG8_BAR; PG8_WAIT_L(0); PG8_MMA(0, 1, At, B1); PG8_BAR;
;             PG8_LDA(At, 1, 1); PG8_STAGE(PG8_SA(1, 0), a3, voffA);
;             PG8_BAR; PG8_WAIT_L(0); PG8_MMA(1, 0, At, B0); PG8_BAR; PG8_SCHED;
;             PG8_STAGE(PG8_SB(1, 1), b3 + hstep, voffB);
;             PG8_WAIT_V(6); PG8_BAR; PG8_MMA(1, 1, At, B1); PG8_BAR;
.LBB0_1089:
	s_add_u32 s22, s20, 0xfffc0080
	s_addc_u32 s23, s21, -1
	s_add_i32 s56, 0, 0x10000
	v_add_u32_e32 v142, s56, v163
	ds_read_b128 v[130:133], v142
	ds_read_b128 v[134:137], v142 offset:1024
	ds_read_b128 v[138:141], v142 offset:2048
	ds_read_b128 v[142:145], v142 offset:3072
	s_cmp_eq_u32 s55, 12
	s_cselect_b32 s25, s26, s23
	s_cselect_b32 s24, s27, s22
	s_cselect_b32 s23, s35, s54
	s_cselect_b32 s22, s41, s53
	v_lshl_add_u64 v[186:187], s[20:21], 0, v[174:175]
	s_add_i32 m0, s30, 0xc000
	ds_read_b128 v[146:149], v190
	ds_read_b128 v[150:153], v190 offset:1024
	ds_read_b128 v[154:157], v190 offset:2048
	ds_read_b128 v[178:181], v190 offset:3072
	ds_read_b128 v[182:185], v190 offset:4096
	ds_read_b128 v[192:195], v190 offset:5120
	ds_read_b128 v[212:215], v190 offset:6144
	ds_read_b128 v[216:219], v190 offset:7168
	global_load_lds_dwordx4 v[186:187], off
	v_lshl_add_u64 v[186:187], s[20:21], 0, v[176:177]
	s_add_i32 m0, s30, 0xe000
	s_nop 0
	global_load_lds_dwordx4 v[186:187], off
	s_waitcnt lgkmcnt(8)
	s_barrier
	s_waitcnt lgkmcnt(0)
	s_setprio 1
	s_waitcnt lgkmcnt(0)
	v_mfma_f32_16x16x32_bf16 v[126:129], v[130:133], v[146:149], v[126:129]
	v_mfma_f32_16x16x32_bf16 v[122:125], v[138:141], v[146:149], v[122:125]
	v_mfma_f32_16x16x32_bf16 v[118:121], v[130:133], v[154:157], v[118:121]
	v_mfma_f32_16x16x32_bf16 v[106:109], v[138:141], v[154:157], v[106:109]
	v_mfma_f32_16x16x32_bf16 v[102:105], v[130:133], v[182:185], v[102:105]
	v_mfma_f32_16x16x32_bf16 v[90:93], v[138:141], v[182:185], v[90:93]
	v_mfma_f32_16x16x32_bf16 v[86:89], v[130:133], v[212:215], v[86:89]
	v_mfma_f32_16x16x32_bf16 v[74:77], v[138:141], v[212:215], v[74:77]
	v_mfma_f32_16x16x32_bf16 v[126:129], v[134:137], v[150:153], v[126:129]
	v_mfma_f32_16x16x32_bf16 v[122:125], v[142:145], v[150:153], v[122:125]
	v_mfma_f32_16x16x32_bf16 v[118:121], v[134:137], v[178:181], v[118:121]
	v_mfma_f32_16x16x32_bf16 v[106:109], v[142:145], v[178:181], v[106:109]
	v_mfma_f32_16x16x32_bf16 v[102:105], v[134:137], v[192:195], v[102:105]
	v_mfma_f32_16x16x32_bf16 v[90:93], v[142:145], v[192:195], v[90:93]
	v_mfma_f32_16x16x32_bf16 v[86:89], v[134:137], v[216:219], v[86:89]
	v_mfma_f32_16x16x32_bf16 v[74:77], v[142:145], v[216:219], v[74:77]
	s_setprio 0
	s_barrier
	s_add_i32 s58, 0, 0x14000
	v_add_u32_e32 v186, s58, v163
	s_add_i32 s56, s56, s29
	ds_read_b128 v[220:223], v186
	ds_read_b128 v[224:227], v186 offset:1024
	ds_read_b128 v[228:231], v186 offset:2048
	ds_read_b128 v[232:235], v186 offset:3072
	v_lshl_add_u64 v[186:187], s[22:23], 0, v[0:1]
	s_mov_b32 m0, s56
	v_lshl_add_u64 v[196:197], s[22:23], 0, v[158:159]
	global_load_lds_dwordx4 v[186:187], off
	s_add_i32 m0, s56, 0x2000
	s_nop 0
	global_load_lds_dwordx4 v[196:197], off
	s_barrier
	s_waitcnt lgkmcnt(0)
	s_setprio 1
	s_waitcnt lgkmcnt(0)
	v_mfma_f32_16x16x32_bf16 v[114:117], v[220:223], v[146:149], v[114:117]
	v_mfma_f32_16x16x32_bf16 v[110:113], v[228:231], v[146:149], v[110:113]
	v_mfma_f32_16x16x32_bf16 v[98:101], v[220:223], v[154:157], v[98:101]
	v_mfma_f32_16x16x32_bf16 v[94:97], v[228:231], v[154:157], v[94:97]
	v_mfma_f32_16x16x32_bf16 v[82:85], v[220:223], v[182:185], v[82:85]
	v_mfma_f32_16x16x32_bf16 v[78:81], v[228:231], v[182:185], v[78:81]
	v_mfma_f32_16x16x32_bf16 v[70:73], v[220:223], v[212:215], v[70:73]
	v_mfma_f32_16x16x32_bf16 v[66:69], v[228:231], v[212:215], v[66:69]
	v_mfma_f32_16x16x32_bf16 v[114:117], v[224:227], v[150:153], v[114:117]
	v_mfma_f32_16x16x32_bf16 v[110:113], v[232:235], v[150:153], v[110:113]
	v_mfma_f32_16x16x32_bf16 v[98:101], v[224:227], v[178:181], v[98:101]
	v_mfma_f32_16x16x32_bf16 v[94:97], v[232:235], v[178:181], v[94:97]
	v_mfma_f32_16x16x32_bf16 v[82:85], v[224:227], v[192:195], v[82:85]
	v_mfma_f32_16x16x32_bf16 v[78:81], v[232:235], v[192:195], v[78:81]
	v_mfma_f32_16x16x32_bf16 v[70:73], v[224:227], v[216:219], v[70:73]
	v_mfma_f32_16x16x32_bf16 v[66:69], v[232:235], v[216:219], v[66:69]
	s_setprio 0
	s_mov_b32 m0, s30
	v_lshl_add_u64 v[236:237], s[24:25], 0, v[172:173]
	s_barrier
	ds_read_b128 v[146:149], v190 offset:16384
	ds_read_b128 v[150:153], v190 offset:17408
	ds_read_b128 v[154:157], v190 offset:18432
	ds_read_b128 v[178:181], v190 offset:19456
	ds_read_b128 v[182:185], v190 offset:20480
	ds_read_b128 v[192:195], v190 offset:21504
	ds_read_b128 v[212:215], v190 offset:22528
	ds_read_b128 v[216:219], v190 offset:23552
	global_load_lds_dwordx4 v[236:237], off
	v_lshl_add_u64 v[238:239], s[24:25], 0, v[160:161]
	s_mov_b32 m0, s44
	s_nop 0
	global_load_lds_dwordx4 v[238:239], off
	s_barrier
	s_waitcnt lgkmcnt(0)
	s_setprio 1
	s_waitcnt lgkmcnt(0)
	v_mfma_f32_16x16x32_bf16 v[62:65], v[130:133], v[146:149], v[62:65]
	v_mfma_f32_16x16x32_bf16 v[58:61], v[138:141], v[146:149], v[58:61]
	v_mfma_f32_16x16x32_bf16 v[54:57], v[130:133], v[154:157], v[54:57]
	v_mfma_f32_16x16x32_bf16 v[42:45], v[138:141], v[154:157], v[42:45]
	v_mfma_f32_16x16x32_bf16 v[38:41], v[130:133], v[182:185], v[38:41]
	v_mfma_f32_16x16x32_bf16 v[26:29], v[138:141], v[182:185], v[26:29]
	v_mfma_f32_16x16x32_bf16 v[22:25], v[130:133], v[212:215], v[22:25]
	v_mfma_f32_16x16x32_bf16 v[10:13], v[138:141], v[212:215], v[10:13]
	v_mfma_f32_16x16x32_bf16 v[62:65], v[134:137], v[150:153], v[62:65]
	v_mfma_f32_16x16x32_bf16 v[58:61], v[142:145], v[150:153], v[58:61]
	v_mfma_f32_16x16x32_bf16 v[54:57], v[134:137], v[178:181], v[54:57]
	v_mfma_f32_16x16x32_bf16 v[42:45], v[142:145], v[178:181], v[42:45]
	v_mfma_f32_16x16x32_bf16 v[38:41], v[134:137], v[192:195], v[38:41]
	v_mfma_f32_16x16x32_bf16 v[26:29], v[142:145], v[192:195], v[26:29]
	v_mfma_f32_16x16x32_bf16 v[22:25], v[134:137], v[216:219], v[22:25]
	v_mfma_f32_16x16x32_bf16 v[10:13], v[142:145], v[216:219], v[10:13]
	s_setprio 0
	s_barrier
; #define PG8_STAGE(bufoff, gbase, voff) do { _Pragma("unroll") for (int _i = 0; _i < 2; ++_i) \
;         __builtin_amdgcn_global_load_lds((const unsigned*)((const char*)(gbase) + (voff)[_i]), (LAS unsigned*)(lds + (bufoff) + ldsw + _i * 8192), 16, 0, 0); } while (0)
; #define PG8_LDA(dst, b, h) do { _Pragma("unroll") for (int m = 0; m < 4; ++m) _Pragma("unroll") for (int k = 0; k < 2; ++k) dst[m][k] = *(const LAS bf16x8*)(lds + PG8_SA(b, h) + aoff + m * 2048 + k * 1024); } while (0)
; #define PG8_WAIT_V(n) asm volatile("s_waitcnt vmcnt(" #n ")" ::: "memory")
; #define PG8_WAIT_L(n) asm volatile("s_waitcnt lgkmcnt(" #n ")" ::: "memory")
; template <class Epi, class Sched>
; __device__ __forceinline__ void gemm_phase(LAS unsigned char* lds, const Gemm g, const Sched& S, const Epi& E) {
;     ...
;         for (int t = 0; t < nt; t += 2) {
;             const bool last = (t == nt - 2);
;             const char* a1 = cA + (size_t)(t + 1) * kstep;
;             const char* a2 = last ? nA : cA + (size_t)(t + 2) * kstep; const char* b2 = last ? nB : cB + (size_t)(t + 2) * kstep;
;             const char* a3 = a2 + kstep; const char* b3 = b2 + kstep;
;             PG8_LDB(B0, 0, 0); PG8_SCHED; PG8_LDA(At, 0, 0); PG8_STAGE(PG8_SA(1, 1), a1 + hstep, voffA);
;             PG8_WAIT_L(8); PG8_BAR; PG8_WAIT_L(0); PG8_MMA(0, 0, At, B0); PG8_BAR; PG8_SCHED;
;             PG8_LDB(B1, 0, 1); PG8_STAGE(PG8_SB(0, 0), b2, voffB);
;             PG8_BAR; PG8_WAIT_L(0); PG8_MMA(0, 1, At, B1); PG8_BAR;
;             PG8_LDA(At, 0, 1); PG8_STAGE(PG8_SA(0, 0), a2, voffA);
;             PG8_BAR; PG8_WAIT_L(0); PG8_MMA(1, 0, At, B0); PG8_BAR; PG8_SCHED;
;             PG8_STAGE(PG8_SB(0, 1), b2 + hstep, voffB);
;             PG8_WAIT_V(6); PG8_BAR; PG8_MMA(1, 1, At, B1); PG8_BAR;
;             PG8_LDB(B0, 1, 0); PG8_SCHED; PG8_LDA(At, 1, 0); PG8_STAGE(PG8_SA(0, 1), a2 + hstep, voffA);
;             PG8_WAIT_L(8); PG8_BAR; PG8_WAIT_L(0); PG8_MMA(0, 0, At, B0); PG8_BAR; PG8_SCHED;
;             PG8_LDB(B1, 1, 1); PG8_STAGE(PG8_SB(1, 0), b3, voffB);
;             PG8_BAR; PG8_WAIT_L(0); PG8_MMA(0, 1, At, B1); PG8_BAR;
;             PG8_LDA(At, 1, 1); PG8_STAGE(PG8_SA(1, 0), a3, voffA);
;             PG8_BAR; PG8_WAIT_L(0); PG8_MMA(1, 0, At, B0); PG8_BAR; PG8_SCHED;
;             PG8_STAGE(PG8_SB(1, 1), b3 + hstep, voffB);
;             PG8_WAIT_V(6); PG8_BAR; PG8_MMA(1, 1, At, B1); PG8_BAR;
	s_add_u32 s56, s22, 0x40000
	s_addc_u32 s57, s23, 0
	s_add_i32 s58, s58, s29
	v_lshl_add_u64 v[130:131], s[56:57], 0, v[0:1]
	s_mov_b32 m0, s58
	s_nop 0
	global_load_lds_dwordx4 v[130:131], off
	v_lshl_add_u64 v[130:131], s[56:57], 0, v[158:159]
	s_add_i32 m0, s58, 0x2000
	s_nop 0
	global_load_lds_dwordx4 v[130:131], off
	s_waitcnt vmcnt(6)
	s_barrier
	s_setprio 1
	v_mfma_f32_16x16x32_bf16 v[50:53], v[220:223], v[146:149], v[50:53]
	v_mfma_f32_16x16x32_bf16 v[46:49], v[228:231], v[146:149], v[46:49]
	v_mfma_f32_16x16x32_bf16 v[34:37], v[220:223], v[154:157], v[34:37]
	v_mfma_f32_16x16x32_bf16 v[30:33], v[228:231], v[154:157], v[30:33]
	v_mfma_f32_16x16x32_bf16 v[18:21], v[220:223], v[182:185], v[18:21]
	v_mfma_f32_16x16x32_bf16 v[14:17], v[228:231], v[182:185], v[14:17]
	v_mfma_f32_16x16x32_bf16 v[6:9], v[220:223], v[212:215], v[6:9]
	v_mfma_f32_16x16x32_bf16 v[2:5], v[228:231], v[212:215], v[2:5]
	v_mfma_f32_16x16x32_bf16 v[50:53], v[224:227], v[150:153], v[50:53]
	v_mfma_f32_16x16x32_bf16 v[46:49], v[232:235], v[150:153], v[46:49]
	v_mfma_f32_16x16x32_bf16 v[34:37], v[224:227], v[178:181], v[34:37]
	v_mfma_f32_16x16x32_bf16 v[30:33], v[232:235], v[178:181], v[30:33]
	v_mfma_f32_16x16x32_bf16 v[18:21], v[224:227], v[192:195], v[18:21]
	v_mfma_f32_16x16x32_bf16 v[14:17], v[232:235], v[192:195], v[14:17]
	v_mfma_f32_16x16x32_bf16 v[6:9], v[224:227], v[216:219], v[6:9]
	v_mfma_f32_16x16x32_bf16 v[2:5], v[232:235], v[216:219], v[2:5]
	s_setprio 0
	s_add_i32 s56, 0, 0x18000
	v_add_u32_e32 v142, s56, v163
	s_barrier
	ds_read_b128 v[130:133], v142
	ds_read_b128 v[134:137], v142 offset:1024
	ds_read_b128 v[138:141], v142 offset:2048
	ds_read_b128 v[142:145], v142 offset:3072
	s_add_u32 s24, s24, 0x40000
	s_addc_u32 s25, s25, 0
	s_mov_b32 m0, s45
	v_lshl_add_u64 v[220:221], s[24:25], 0, v[172:173]
	ds_read_b128 v[146:149], v190 offset:32768
	ds_read_b128 v[150:153], v190 offset:33792
	ds_read_b128 v[154:157], v190 offset:34816
	ds_read_b128 v[178:181], v190 offset:35840
	ds_read_b128 v[182:185], v190 offset:36864
	ds_read_b128 v[192:195], v190 offset:37888
	ds_read_b128 v[212:215], v190 offset:38912
	ds_read_b128 v[216:219], v190 offset:39936
	global_load_lds_dwordx4 v[220:221], off
	v_lshl_add_u64 v[220:221], s[24:25], 0, v[160:161]
	s_mov_b32 m0, s48
	s_nop 0
	global_load_lds_dwordx4 v[220:221], off
	s_waitcnt lgkmcnt(8)
	s_barrier
	s_waitcnt lgkmcnt(0)
	s_setprio 1
	s_waitcnt lgkmcnt(0)
	v_mfma_f32_16x16x32_bf16 v[126:129], v[130:133], v[146:149], v[126:129]
	v_mfma_f32_16x16x32_bf16 v[122:125], v[138:141], v[146:149], v[122:125]
	v_mfma_f32_16x16x32_bf16 v[118:121], v[130:133], v[154:157], v[118:121]
	v_mfma_f32_16x16x32_bf16 v[106:109], v[138:141], v[154:157], v[106:109]
	v_mfma_f32_16x16x32_bf16 v[102:105], v[130:133], v[182:185], v[102:105]
	v_mfma_f32_16x16x32_bf16 v[90:93], v[138:141], v[182:185], v[90:93]
	v_mfma_f32_16x16x32_bf16 v[86:89], v[130:133], v[212:215], v[86:89]
	v_mfma_f32_16x16x32_bf16 v[74:77], v[138:141], v[212:215], v[74:77]
	v_mfma_f32_16x16x32_bf16 v[126:129], v[134:137], v[150:153], v[126:129]
	v_mfma_f32_16x16x32_bf16 v[122:125], v[142:145], v[150:153], v[122:125]
	v_mfma_f32_16x16x32_bf16 v[118:121], v[134:137], v[178:181], v[118:121]
	v_mfma_f32_16x16x32_bf16 v[106:109], v[142:145], v[178:181], v[106:109]
	v_mfma_f32_16x16x32_bf16 v[102:105], v[134:137], v[192:195], v[102:105]
	v_mfma_f32_16x16x32_bf16 v[90:93], v[142:145], v[192:195], v[90:93]
	v_mfma_f32_16x16x32_bf16 v[86:89], v[134:137], v[216:219], v[86:89]
	v_mfma_f32_16x16x32_bf16 v[74:77], v[142:145], v[216:219], v[74:77]
	s_setprio 0
	s_barrier
	s_add_i32 s24, 0, 0x1c000
	s_add_i32 s25, s56, s29
	v_add_u32_e32 v191, s24, v163
	v_lshl_add_u64 v[186:187], v[186:187], 0, s[2:3]
	s_mov_b32 m0, s25
	ds_read_b128 v[220:223], v191
	ds_read_b128 v[224:227], v191 offset:1024
	ds_read_b128 v[228:231], v191 offset:2048
	ds_read_b128 v[232:235], v191 offset:3072
	global_load_lds_dwordx4 v[186:187], off
	v_lshl_add_u64 v[186:187], v[196:197], 0, s[2:3]
	s_add_i32 m0, s25, 0x2000
	s_nop 0
	global_load_lds_dwordx4 v[186:187], off
	s_barrier
	s_waitcnt lgkmcnt(0)
	s_setprio 1
	s_waitcnt lgkmcnt(0)
	v_mfma_f32_16x16x32_bf16 v[114:117], v[220:223], v[146:149], v[114:117]
	v_mfma_f32_16x16x32_bf16 v[110:113], v[228:231], v[146:149], v[110:113]
	v_mfma_f32_16x16x32_bf16 v[98:101], v[220:223], v[154:157], v[98:101]
	v_mfma_f32_16x16x32_bf16 v[94:97], v[228:231], v[154:157], v[94:97]
	v_mfma_f32_16x16x32_bf16 v[82:85], v[220:223], v[182:185], v[82:85]
	v_mfma_f32_16x16x32_bf16 v[78:81], v[228:231], v[182:185], v[78:81]
	v_mfma_f32_16x16x32_bf16 v[70:73], v[220:223], v[212:215], v[70:73]
	v_mfma_f32_16x16x32_bf16 v[66:69], v[228:231], v[212:215], v[66:69]
	v_mfma_f32_16x16x32_bf16 v[114:117], v[224:227], v[150:153], v[114:117]
	v_mfma_f32_16x16x32_bf16 v[110:113], v[232:235], v[150:153], v[110:113]
	v_mfma_f32_16x16x32_bf16 v[98:101], v[224:227], v[178:181], v[98:101]
	v_mfma_f32_16x16x32_bf16 v[94:97], v[232:235], v[178:181], v[94:97]
	v_mfma_f32_16x16x32_bf16 v[82:85], v[224:227], v[192:195], v[82:85]
	v_mfma_f32_16x16x32_bf16 v[78:81], v[232:235], v[192:195], v[78:81]
	v_mfma_f32_16x16x32_bf16 v[70:73], v[224:227], v[216:219], v[70:73]
	v_mfma_f32_16x16x32_bf16 v[66:69], v[232:235], v[216:219], v[66:69]
	s_setprio 0
	s_mov_b32 m0, s49
	v_lshl_add_u64 v[186:187], v[236:237], 0, s[2:3]
	s_barrier
	ds_read_b128 v[146:149], v190 offset:49152
	ds_read_b128 v[150:153], v190 offset:50176
	ds_read_b128 v[154:157], v190 offset:51200
	ds_read_b128 v[178:181], v190 offset:52224
	ds_read_b128 v[182:185], v190 offset:53248
	ds_read_b128 v[192:195], v190 offset:54272
	ds_read_b128 v[212:215], v190 offset:55296
	ds_read_b128 v[216:219], v190 offset:56320
	global_load_lds_dwordx4 v[186:187], off
	v_lshl_add_u64 v[186:187], v[238:239], 0, s[2:3]
	s_mov_b32 m0, s50
	s_nop 0
	global_load_lds_dwordx4 v[186:187], off
	s_barrier
; #define PG8_STAGE(bufoff, gbase, voff) do { _Pragma("unroll") for (int _i = 0; _i < 2; ++_i) \
;         __builtin_amdgcn_global_load_lds((const unsigned*)((const char*)(gbase) + (voff)[_i]), (LAS unsigned*)(lds + (bufoff) + ldsw + _i * 8192), 16, 0, 0); } while (0)
; #define PG8_LDA(dst, b, h) do { _Pragma("unroll") for (int m = 0; m < 4; ++m) _Pragma("unroll") for (int k = 0; k < 2; ++k) dst[m][k] = *(const LAS bf16x8*)(lds + PG8_SA(b, h) + aoff + m * 2048 + k * 1024); } while (0)
; #define PG8_MMA(ai, bj, At, Bt) do { __builtin_amdgcn_s_setprio(1); _Pragma("unroll") for (int m = 0; m < 4; ++m) _Pragma("unroll") for (int n = 0; n < 2; ++n) _Pragma("unroll") for (int k = 0; k < 2; ++k) \
;         acc[ai][bj][m][n] = __builtin_amdgcn_mfma_f32_16x16x32_bf16(Bt[n][k], At[m][k], acc[ai][bj][m][n], 0, 0, 0); __builtin_amdgcn_s_setprio(0); } while (0)
; #define PG8_WAIT_V(n) asm volatile("s_waitcnt vmcnt(" #n ")" ::: "memory")
; #define PG8_WAIT_L(n) asm volatile("s_waitcnt lgkmcnt(" #n ")" ::: "memory")
; #define PG8_BAR __builtin_amdgcn_s_barrier()
; #define PG8_SCHED __builtin_amdgcn_sched_barrier(0)
; template <class Epi, class Sched>
; __device__ __forceinline__ void gemm_phase(LAS unsigned char* lds, const Gemm g, const Sched& S, const Epi& E) {
;     ...
;             PG8_BAR; PG8_WAIT_L(0); PG8_MMA(0, 1, At, B1); PG8_BAR;
;             PG8_LDA(At, 1, 1); PG8_STAGE(PG8_SA(1, 0), a3, voffA);
;             PG8_BAR; PG8_WAIT_L(0); PG8_MMA(1, 0, At, B0); PG8_BAR; PG8_SCHED;
;             PG8_STAGE(PG8_SB(1, 1), b3 + hstep, voffB);
;             PG8_WAIT_V(6); PG8_BAR; PG8_MMA(1, 1, At, B1); PG8_BAR;
;     __device__ __forceinline__ void operator()(f32x4 (&acc)[2][2][4][2], const pg8::Unit& u, int wr, int wc, int fr, int fq) const {
;         const int row0 = tok0 + u.pm * 256 + wr * 64 + fr, col0 = u.pn * 256 + wc * 32 + 8 * fq;
; #pragma unroll
;         for (int ai = 0; ai < 2; ++ai) {
;             f32x4 rv[4][2][2];
; #pragma unroll
;             for (int m = 0; m < 4; ++m) { const size_t ro = (size_t)(row0 + ai * 128 + m * 16) * DM + col0;
; #pragma unroll
;                 for (int bj = 0; bj < 2; ++bj)
; #pragma unroll
;                     for (int n = 0; n < 2; ++n) rv[m][bj][n] = *(const f32x4*)(resid + ro + bj * 128 + n * 4); }
	s_waitcnt lgkmcnt(0)
	s_setprio 1
	s_waitcnt lgkmcnt(0)
	v_mfma_f32_16x16x32_bf16 v[62:65], v[130:133], v[146:149], v[62:65]
	v_mfma_f32_16x16x32_bf16 v[58:61], v[138:141], v[146:149], v[58:61]
	v_mfma_f32_16x16x32_bf16 v[54:57], v[130:133], v[154:157], v[54:57]
	v_mfma_f32_16x16x32_bf16 v[42:45], v[138:141], v[154:157], v[42:45]
	v_mfma_f32_16x16x32_bf16 v[38:41], v[130:133], v[182:185], v[38:41]
	v_mfma_f32_16x16x32_bf16 v[26:29], v[138:141], v[182:185], v[26:29]
	v_mfma_f32_16x16x32_bf16 v[22:25], v[130:133], v[212:215], v[22:25]
	v_mfma_f32_16x16x32_bf16 v[10:13], v[138:141], v[212:215], v[10:13]
	v_mfma_f32_16x16x32_bf16 v[62:65], v[134:137], v[150:153], v[62:65]
	v_mfma_f32_16x16x32_bf16 v[58:61], v[142:145], v[150:153], v[58:61]
	v_mfma_f32_16x16x32_bf16 v[54:57], v[134:137], v[178:181], v[54:57]
	v_mfma_f32_16x16x32_bf16 v[42:45], v[142:145], v[178:181], v[42:45]
	v_mfma_f32_16x16x32_bf16 v[38:41], v[134:137], v[192:195], v[38:41]
	v_mfma_f32_16x16x32_bf16 v[26:29], v[142:145], v[192:195], v[26:29]
	v_mfma_f32_16x16x32_bf16 v[22:25], v[134:137], v[216:219], v[22:25]
	v_mfma_f32_16x16x32_bf16 v[10:13], v[142:145], v[216:219], v[10:13]
	s_setprio 0
	s_barrier
	s_add_u32 s22, s22, 0x40080
	s_addc_u32 s23, s23, 0
	s_add_i32 s24, s24, s29
	v_lshl_add_u64 v[130:131], s[22:23], 0, v[0:1]
	s_mov_b32 m0, s24
	s_nop 0
	global_load_lds_dwordx4 v[130:131], off
	v_lshl_add_u64 v[130:131], s[22:23], 0, v[158:159]
	s_add_i32 m0, s24, 0x2000
	s_nop 0
	global_load_lds_dwordx4 v[130:131], off
	s_waitcnt vmcnt(6)
	s_barrier
	s_setprio 1
	v_mfma_f32_16x16x32_bf16 v[50:53], v[220:223], v[146:149], v[50:53]
	v_mfma_f32_16x16x32_bf16 v[46:49], v[228:231], v[146:149], v[46:49]
	v_mfma_f32_16x16x32_bf16 v[34:37], v[220:223], v[154:157], v[34:37]
	v_mfma_f32_16x16x32_bf16 v[30:33], v[228:231], v[154:157], v[30:33]
	v_mfma_f32_16x16x32_bf16 v[18:21], v[220:223], v[182:185], v[18:21]
	v_mfma_f32_16x16x32_bf16 v[14:17], v[228:231], v[182:185], v[14:17]
	v_mfma_f32_16x16x32_bf16 v[6:9], v[220:223], v[212:215], v[6:9]
	v_mfma_f32_16x16x32_bf16 v[2:5], v[228:231], v[212:215], v[2:5]
	v_mfma_f32_16x16x32_bf16 v[50:53], v[224:227], v[150:153], v[50:53]
	v_mfma_f32_16x16x32_bf16 v[46:49], v[232:235], v[150:153], v[46:49]
	v_mfma_f32_16x16x32_bf16 v[34:37], v[224:227], v[178:181], v[34:37]
	v_mfma_f32_16x16x32_bf16 v[30:33], v[232:235], v[178:181], v[30:33]
	v_mfma_f32_16x16x32_bf16 v[18:21], v[224:227], v[192:195], v[18:21]
	v_mfma_f32_16x16x32_bf16 v[14:17], v[232:235], v[192:195], v[14:17]
	v_mfma_f32_16x16x32_bf16 v[6:9], v[224:227], v[216:219], v[6:9]
	v_mfma_f32_16x16x32_bf16 v[2:5], v[232:235], v[216:219], v[2:5]
	s_setprio 0
	s_add_i32 s55, s55, 2
	s_add_u32 s20, s20, 0x100
	s_addc_u32 s21, s21, 0
	s_add_u32 s53, s53, 0x100
	s_addc_u32 s54, s54, 0
	s_cmp_gt_u32 s55, 13
	s_barrier
	s_cbranch_scc0 .LBB0_1089
	v_lshl_or_b32 v132, s37, 8, v189
	v_lshl_add_u32 v130, s52, 8, v188
	v_ashrrev_i32_e32 v133, 31, v132
	v_lshlrev_b64 v[178:179], 2, v[132:133]
	v_bfe_u32 v246, v198, 2, 4
	v_and_b32_e32 v247, 15, v198
	v_sub_u32_e32 v246, v246, v247
	v_and_b32_e32 v247, 3, v198
	v_bfe_u32 v245, v198, 4, 2
	v_sub_u32_e32 v247, v247, v245
	v_lshlrev_b32_e32 v246, 12, v246
	v_lshl_add_u32 v246, v247, 5, v246
	v_ashrrev_i32_e32 v247, 31, v246
	v_lshl_add_u64 v[178:179], v[178:179], 0, v[246:247]
	v_ashrrev_i32_e32 v131, 31, v130
	v_lshl_add_u64 v[180:181], s[0:1], 0, v[178:179]
	v_lshlrev_b64 v[182:183], 12, v[130:131]
	v_lshl_add_u64 v[132:133], v[180:181], 0, v[182:183]
	global_load_dwordx4 v[192:195], v[132:133], off offset:16
	global_load_dwordx4 v[212:215], v[132:133], off
	global_load_dwordx4 v[216:219], v[132:133], off offset:528
	global_load_dwordx4 v[220:223], v[132:133], off offset:512
	v_or_b32_e32 v132, 16, v130
	v_ashrrev_i32_e32 v133, 31, v132
	v_lshlrev_b64 v[196:197], 12, v[132:133]
	v_lshl_add_u64 v[132:133], v[180:181], 0, v[196:197]
	global_load_dwordx4 v[224:227], v[132:133], off offset:16
	global_load_dwordx4 v[228:231], v[132:133], off
	global_load_dwordx4 v[232:235], v[132:133], off offset:528
	global_load_dwordx4 v[236:239], v[132:133], off offset:512
	v_or_b32_e32 v132, 32, v130
	v_ashrrev_i32_e32 v133, 31, v132
	v_lshlrev_b64 v[186:187], 12, v[132:133]
	v_or_b32_e32 v130, 48, v130
	v_lshl_add_u64 v[132:133], v[180:181], 0, v[186:187]
	v_ashrrev_i32_e32 v131, 31, v130
	global_load_dwordx4 v[142:145], v[132:133], off offset:16
	global_load_dwordx4 v[240:243], v[132:133], off
	global_load_dwordx4 v[146:149], v[132:133], off offset:528
	global_load_dwordx4 v[150:153], v[132:133], off offset:512
	v_lshlrev_b64 v[184:185], 12, v[130:131]
	v_lshl_add_u64 v[134:135], v[180:181], 0, v[184:185]
	global_load_dwordx4 v[138:141], v[134:135], off offset:16
	global_load_dwordx4 v[154:157], v[134:135], off
	global_load_dwordx4 v[130:133], v[134:135], off offset:528
	s_nop 0
	global_load_dwordx4 v[134:137], v[134:135], off offset:512
	v_readlane_b32 s52, v253, 22
	v_readlane_b32 s66, v253, 36
	v_readlane_b32 s67, v253, 37
	s_mov_b64 s[20:21], 0x80000
	s_and_b64 vcc, exec, s[38:39]
	s_mov_b32 s37, s34
	s_mov_b32 s52, s40
	s_mov_b64 s[22:23], s[46:47]
	v_readlane_b32 s53, v253, 23
	v_readlane_b32 s54, v253, 24
	v_readlane_b32 s55, v253, 25
	v_readlane_b32 s56, v253, 26
	v_readlane_b32 s57, v253, 27
	v_readlane_b32 s58, v253, 28
	v_readlane_b32 s59, v253, 29
	v_readlane_b32 s60, v253, 30
	v_readlane_b32 s61, v253, 31
	v_readlane_b32 s62, v253, 32
	v_readlane_b32 s63, v253, 33
	v_readlane_b32 s64, v253, 34
	v_readlane_b32 s65, v253, 35
	v_and_b32_e32 v244, 3, v198
	v_bfe_u32 v245, v198, 2, 4
	v_lshl_add_u32 v244, v244, 4, v245
	v_lshlrev_b32_e32 v244, 2, v244
	ds_bpermute_b32 v129, v244, v129
	ds_bpermute_b32 v128, v244, v128
	ds_bpermute_b32 v127, v244, v127
	ds_bpermute_b32 v126, v244, v126
	ds_bpermute_b32 v125, v244, v125
	ds_bpermute_b32 v124, v244, v124
	ds_bpermute_b32 v123, v244, v123
	ds_bpermute_b32 v122, v244, v122
	ds_bpermute_b32 v121, v244, v121
	ds_bpermute_b32 v120, v244, v120
	ds_bpermute_b32 v119, v244, v119
	ds_bpermute_b32 v118, v244, v118
	ds_bpermute_b32 v117, v244, v117
	ds_bpermute_b32 v116, v244, v116
	ds_bpermute_b32 v115, v244, v115
	s_waitcnt lgkmcnt(7)
;     __device__ __forceinline__ void operator()(f32x4 (&acc)[2][2][4][2], const pg8::Unit& u, int wr, int wc, int fr, int fq) const {
;         const int row0 = tok0 + u.pm * 256 + wr * 64 + fr, col0 = u.pn * 256 + wc * 32 + 8 * fq;
; #pragma unroll
;         for (int ai = 0; ai < 2; ++ai) {
;             f32x4 rv[4][2][2];
; #pragma unroll
;             for (int m = 0; m < 4; ++m) { const size_t ro = (size_t)(row0 + ai * 128 + m * 16) * DM + col0;
; #pragma unroll
;                 for (int bj = 0; bj < 2; ++bj)
; #pragma unroll
;                     for (int n = 0; n < 2; ++n) rv[m][bj][n] = *(const f32x4*)(resid + ro + bj * 128 + n * 4); }
; #pragma unroll
;             for (int m = 0; m < 4; ++m) { const size_t ro = (size_t)(row0 + ai * 128 + m * 16) * DM + col0;
; #pragma unroll
;                 for (int bj = 0; bj < 2; ++bj)
; #pragma unroll
;                     for (int n = 0; n < 2; ++n) *(f32x4*)(out + ro + bj * 128 + n * 4) = rv[m][bj][n] + acc[ai][bj][m][n]; }
	ds_bpermute_b32 v114, v244, v114
	ds_bpermute_b32 v113, v244, v113
	ds_bpermute_b32 v112, v244, v112
	ds_bpermute_b32 v111, v244, v111
	ds_bpermute_b32 v110, v244, v110
	ds_bpermute_b32 v109, v244, v109
	ds_bpermute_b32 v108, v244, v108
	ds_bpermute_b32 v107, v244, v107
	s_waitcnt lgkmcnt(7)
	ds_bpermute_b32 v106, v244, v106
	ds_bpermute_b32 v105, v244, v105
	ds_bpermute_b32 v104, v244, v104
	ds_bpermute_b32 v103, v244, v103
	ds_bpermute_b32 v102, v244, v102
	ds_bpermute_b32 v101, v244, v101
	ds_bpermute_b32 v100, v244, v100
	ds_bpermute_b32 v99, v244, v99
	s_waitcnt lgkmcnt(7)
	ds_bpermute_b32 v98, v244, v98
	ds_bpermute_b32 v97, v244, v97
	ds_bpermute_b32 v96, v244, v96
	ds_bpermute_b32 v95, v244, v95
	ds_bpermute_b32 v94, v244, v94
	ds_bpermute_b32 v93, v244, v93
	ds_bpermute_b32 v92, v244, v92
	ds_bpermute_b32 v91, v244, v91
	s_waitcnt lgkmcnt(7)
	ds_bpermute_b32 v90, v244, v90
	ds_bpermute_b32 v89, v244, v89
	ds_bpermute_b32 v88, v244, v88
	ds_bpermute_b32 v87, v244, v87
	ds_bpermute_b32 v86, v244, v86
	ds_bpermute_b32 v85, v244, v85
	ds_bpermute_b32 v84, v244, v84
	ds_bpermute_b32 v83, v244, v83
	s_waitcnt lgkmcnt(7)
	ds_bpermute_b32 v82, v244, v82
	ds_bpermute_b32 v81, v244, v81
	ds_bpermute_b32 v80, v244, v80
	ds_bpermute_b32 v79, v244, v79
	ds_bpermute_b32 v78, v244, v78
	ds_bpermute_b32 v77, v244, v77
	ds_bpermute_b32 v76, v244, v76
	ds_bpermute_b32 v75, v244, v75
	s_waitcnt lgkmcnt(7)
	ds_bpermute_b32 v74, v244, v74
	ds_bpermute_b32 v73, v244, v73
	ds_bpermute_b32 v72, v244, v72
	ds_bpermute_b32 v71, v244, v71
	ds_bpermute_b32 v70, v244, v70
	ds_bpermute_b32 v69, v244, v69
	ds_bpermute_b32 v68, v244, v68
	ds_bpermute_b32 v67, v244, v67
	s_waitcnt lgkmcnt(7)
	ds_bpermute_b32 v66, v244, v66
	ds_bpermute_b32 v65, v244, v65
	ds_bpermute_b32 v64, v244, v64
	ds_bpermute_b32 v63, v244, v63
	ds_bpermute_b32 v62, v244, v62
	ds_bpermute_b32 v61, v244, v61
	ds_bpermute_b32 v60, v244, v60
	ds_bpermute_b32 v59, v244, v59
	s_waitcnt lgkmcnt(7)
	ds_bpermute_b32 v58, v244, v58
	ds_bpermute_b32 v57, v244, v57
	ds_bpermute_b32 v56, v244, v56
	ds_bpermute_b32 v55, v244, v55
	ds_bpermute_b32 v54, v244, v54
	ds_bpermute_b32 v53, v244, v53
	ds_bpermute_b32 v52, v244, v52
	ds_bpermute_b32 v51, v244, v51
	s_waitcnt lgkmcnt(7)
	ds_bpermute_b32 v50, v244, v50
	ds_bpermute_b32 v49, v244, v49
	ds_bpermute_b32 v48, v244, v48
	ds_bpermute_b32 v47, v244, v47
	ds_bpermute_b32 v46, v244, v46
	ds_bpermute_b32 v45, v244, v45
	ds_bpermute_b32 v44, v244, v44
	ds_bpermute_b32 v43, v244, v43
	s_waitcnt lgkmcnt(7)
	ds_bpermute_b32 v42, v244, v42
	ds_bpermute_b32 v41, v244, v41
	ds_bpermute_b32 v40, v244, v40
	ds_bpermute_b32 v39, v244, v39
	ds_bpermute_b32 v38, v244, v38
	ds_bpermute_b32 v37, v244, v37
	ds_bpermute_b32 v36, v244, v36
	ds_bpermute_b32 v35, v244, v35
	s_waitcnt lgkmcnt(7)
	ds_bpermute_b32 v34, v244, v34
	ds_bpermute_b32 v33, v244, v33
	ds_bpermute_b32 v32, v244, v32
	ds_bpermute_b32 v31, v244, v31
	ds_bpermute_b32 v30, v244, v30
	ds_bpermute_b32 v29, v244, v29
	ds_bpermute_b32 v28, v244, v28
	ds_bpermute_b32 v27, v244, v27
	s_waitcnt lgkmcnt(7)
	ds_bpermute_b32 v26, v244, v26
	ds_bpermute_b32 v25, v244, v25
	ds_bpermute_b32 v24, v244, v24
	ds_bpermute_b32 v23, v244, v23
	ds_bpermute_b32 v22, v244, v22
	ds_bpermute_b32 v21, v244, v21
	ds_bpermute_b32 v20, v244, v20
	ds_bpermute_b32 v19, v244, v19
	s_waitcnt lgkmcnt(7)
	ds_bpermute_b32 v18, v244, v18
	ds_bpermute_b32 v17, v244, v17
	ds_bpermute_b32 v16, v244, v16
	ds_bpermute_b32 v15, v244, v15
	ds_bpermute_b32 v14, v244, v14
	ds_bpermute_b32 v13, v244, v13
	ds_bpermute_b32 v12, v244, v12
	ds_bpermute_b32 v11, v244, v11
	s_waitcnt lgkmcnt(7)
	ds_bpermute_b32 v10, v244, v10
	ds_bpermute_b32 v9, v244, v9
	ds_bpermute_b32 v8, v244, v8
	ds_bpermute_b32 v7, v244, v7
	ds_bpermute_b32 v6, v244, v6
	ds_bpermute_b32 v5, v244, v5
	ds_bpermute_b32 v4, v244, v4
	ds_bpermute_b32 v3, v244, v3
	s_waitcnt lgkmcnt(7)
	ds_bpermute_b32 v2, v244, v2
	s_waitcnt lgkmcnt(0)
	s_waitcnt vmcnt(0)
;     __device__ __forceinline__ void operator()(f32x4 (&acc)[2][2][4][2], const pg8::Unit& u, int wr, int wc, int fr, int fq) const {
;     ...
;         for (int ai = 0; ai < 2; ++ai) {
;             f32x4 rv[4][2][2];
; #pragma unroll
;             for (int m = 0; m < 4; ++m) { const size_t ro = (size_t)(row0 + ai * 128 + m * 16) * DM + col0;
; #pragma unroll
;                 for (int bj = 0; bj < 2; ++bj)
; #pragma unroll
;                     for (int n = 0; n < 2; ++n) rv[m][bj][n] = *(const f32x4*)(resid + ro + bj * 128 + n * 4); }
; #pragma unroll
;             for (int m = 0; m < 4; ++m) { const size_t ro = (size_t)(row0 + ai * 128 + m * 16) * DM + col0;
; #pragma unroll
;                 for (int bj = 0; bj < 2; ++bj)
; #pragma unroll
;                     for (int n = 0; n < 2; ++n) *(f32x4*)(out + ro + bj * 128 + n * 4) = rv[m][bj][n] + acc[ai][bj][m][n]; }
;         }
	v_pk_add_f32 v[124:125], v[124:125], v[194:195]
	v_pk_add_f32 v[126:127], v[126:127], v[212:213]
	v_lshl_add_u64 v[212:213], s[66:67], 0, v[182:183]
	v_lshl_add_u64 v[212:213], v[212:213], 0, v[178:179]
	v_pk_add_f32 v[116:117], v[116:117], v[222:223]
	v_pk_add_f32 v[114:115], v[114:115], v[220:221]
	global_store_dwordx4 v[212:213], v[114:117], off offset:512
	v_pk_add_f32 v[112:113], v[112:113], v[218:219]
	v_pk_add_f32 v[100:101], v[100:101], v[238:239]
	v_lshl_add_u64 v[114:115], s[66:67], 0, v[196:197]
	v_lshl_add_u64 v[114:115], v[114:115], 0, v[178:179]
	v_pk_add_f32 v[98:99], v[98:99], v[236:237]
	global_store_dwordx4 v[114:115], v[98:101], off offset:512
	v_pk_add_f32 v[110:111], v[110:111], v[216:217]
	v_pk_add_f32 v[96:97], v[96:97], v[234:235]
	v_lshl_add_u64 v[98:99], s[66:67], 0, v[186:187]
	v_lshl_add_u64 v[98:99], v[98:99], 0, v[178:179]
	v_pk_add_f32 v[84:85], v[84:85], v[152:153]
	v_pk_add_f32 v[82:83], v[82:83], v[150:151]
	v_pk_add_f32 v[94:95], v[94:95], v[232:233]
	global_store_dwordx4 v[98:99], v[82:85], off offset:512
	v_pk_add_f32 v[80:81], v[80:81], v[148:149]
	v_pk_add_f32 v[78:79], v[78:79], v[146:147]
	v_lshl_add_u64 v[82:83], s[66:67], 0, v[184:185]
	v_pk_add_f32 v[128:129], v[128:129], v[214:215]
	v_pk_add_f32 v[122:123], v[122:123], v[192:193]
	global_store_dwordx4 v[212:213], v[110:113], off offset:528
	v_pk_add_f32 v[108:109], v[108:109], v[226:227]
	v_pk_add_f32 v[106:107], v[106:107], v[224:225]
	v_pk_add_f32 v[112:113], v[120:121], v[230:231]
	v_pk_add_f32 v[110:111], v[118:119], v[228:229]
	global_store_dwordx4 v[114:115], v[94:97], off offset:528
	v_pk_add_f32 v[92:93], v[92:93], v[144:145]
	v_pk_add_f32 v[90:91], v[90:91], v[142:143]
	v_pk_add_f32 v[96:97], v[104:105], v[242:243]
	v_pk_add_f32 v[94:95], v[102:103], v[240:241]
	global_store_dwordx4 v[98:99], v[78:81], off offset:528
	v_lshl_add_u64 v[82:83], v[82:83], 0, v[178:179]
	v_pk_add_f32 v[76:77], v[76:77], v[140:141]
	v_pk_add_f32 v[80:81], v[88:89], v[156:157]
	v_pk_add_f32 v[78:79], v[86:87], v[154:155]
	v_pk_add_f32 v[74:75], v[74:75], v[138:139]
	v_pk_add_f32 v[72:73], v[72:73], v[136:137]
	v_pk_add_f32 v[70:71], v[70:71], v[134:135]
	v_pk_add_f32 v[68:69], v[68:69], v[132:133]
	v_pk_add_f32 v[66:67], v[66:67], v[130:131]
	v_lshl_add_u64 v[134:135], v[182:183], 0, s[20:21]
	global_store_dwordx4 v[212:213], v[126:129], off
	global_store_dwordx4 v[212:213], v[122:125], off offset:16
	global_store_dwordx4 v[114:115], v[110:113], off
	global_store_dwordx4 v[114:115], v[106:109], off offset:16
	global_store_dwordx4 v[98:99], v[94:97], off
	global_store_dwordx4 v[98:99], v[90:93], off offset:16
	global_store_dwordx4 v[82:83], v[78:81], off
	global_store_dwordx4 v[82:83], v[74:77], off offset:16
	global_store_dwordx4 v[82:83], v[70:73], off offset:512
	global_store_dwordx4 v[82:83], v[66:69], off offset:528
	s_mov_b64 s[20:21], 0x90000
	v_lshl_add_u64 v[136:137], v[182:183], 0, s[20:21]
	v_lshl_add_u64 v[66:67], v[180:181], 0, v[134:135]
	global_load_dwordx4 v[90:93], v[66:67], off offset:16
	global_load_dwordx4 v[94:97], v[66:67], off
	global_load_dwordx4 v[98:101], v[66:67], off offset:528
	global_load_dwordx4 v[102:105], v[66:67], off offset:512
	v_lshl_add_u64 v[66:67], v[180:181], 0, v[136:137]
	s_mov_b64 s[20:21], 0xa0000
	global_load_dwordx4 v[106:109], v[66:67], off offset:16
	global_load_dwordx4 v[110:113], v[66:67], off
	global_load_dwordx4 v[114:117], v[66:67], off offset:528
	global_load_dwordx4 v[118:121], v[66:67], off offset:512
	v_lshl_add_u64 v[88:89], v[182:183], 0, s[20:21]
	v_lshl_add_u64 v[66:67], v[180:181], 0, v[88:89]
	s_mov_b64 s[20:21], 0xb0000
	global_load_dwordx4 v[78:81], v[66:67], off offset:16
	global_load_dwordx4 v[122:125], v[66:67], off
	global_load_dwordx4 v[82:85], v[66:67], off offset:528
	global_load_dwordx4 v[126:129], v[66:67], off offset:512
	v_lshl_add_u64 v[86:87], v[182:183], 0, s[20:21]
	v_lshl_add_u64 v[74:75], v[180:181], 0, v[86:87]
	global_load_dwordx4 v[70:73], v[74:75], off offset:16
	global_load_dwordx4 v[130:133], v[74:75], off
	global_load_dwordx4 v[66:69], v[74:75], off offset:528
	s_nop 0
	global_load_dwordx4 v[74:77], v[74:75], off offset:512
	s_mov_b64 s[20:21], s[42:43]
	s_waitcnt vmcnt(0)
	v_pk_add_f32 v[60:61], v[60:61], v[92:93]
	v_pk_add_f32 v[62:63], v[62:63], v[94:95]
	v_lshl_add_u64 v[94:95], s[66:67], 0, v[134:135]
	v_lshl_add_u64 v[94:95], v[94:95], 0, v[178:179]
	v_pk_add_f32 v[52:53], v[52:53], v[104:105]
	v_pk_add_f32 v[50:51], v[50:51], v[102:103]
	global_store_dwordx4 v[94:95], v[50:53], off offset:512
	v_pk_add_f32 v[36:37], v[36:37], v[120:121]
	v_pk_add_f32 v[34:35], v[34:35], v[118:119]
	v_lshl_add_u64 v[50:51], s[66:67], 0, v[136:137]
	v_lshl_add_u64 v[50:51], v[50:51], 0, v[178:179]
	global_store_dwordx4 v[50:51], v[34:37], off offset:512
	v_pk_add_f32 v[20:21], v[20:21], v[128:129]
	v_pk_add_f32 v[18:19], v[18:19], v[126:127]
	v_lshl_add_u64 v[34:35], s[66:67], 0, v[88:89]
	v_lshl_add_u64 v[34:35], v[34:35], 0, v[178:179]
	v_pk_add_f32 v[48:49], v[48:49], v[100:101]
	v_pk_add_f32 v[46:47], v[46:47], v[98:99]
	v_pk_add_f32 v[32:33], v[32:33], v[116:117]
	v_pk_add_f32 v[30:31], v[30:31], v[114:115]
	global_store_dwordx4 v[34:35], v[18:21], off offset:512
	v_pk_add_f32 v[16:17], v[16:17], v[84:85]
	v_pk_add_f32 v[14:15], v[14:15], v[82:83]
	v_lshl_add_u64 v[18:19], s[66:67], 0, v[86:87]
	v_pk_add_f32 v[64:65], v[64:65], v[96:97]
	v_pk_add_f32 v[58:59], v[58:59], v[90:91]
	global_store_dwordx4 v[94:95], v[46:49], off offset:528
	v_pk_add_f32 v[44:45], v[44:45], v[108:109]
	v_pk_add_f32 v[42:43], v[42:43], v[106:107]
	v_pk_add_f32 v[48:49], v[56:57], v[112:113]
	v_pk_add_f32 v[46:47], v[54:55], v[110:111]
	global_store_dwordx4 v[50:51], v[30:33], off offset:528
	v_pk_add_f32 v[28:29], v[28:29], v[80:81]
	v_pk_add_f32 v[26:27], v[26:27], v[78:79]
	v_pk_add_f32 v[32:33], v[40:41], v[124:125]
	v_pk_add_f32 v[30:31], v[38:39], v[122:123]
	global_store_dwordx4 v[34:35], v[14:17], off offset:528
	v_lshl_add_u64 v[18:19], v[18:19], 0, v[178:179]
	v_pk_add_f32 v[12:13], v[12:13], v[72:73]
	v_pk_add_f32 v[16:17], v[24:25], v[132:133]
	v_pk_add_f32 v[14:15], v[22:23], v[130:131]
	v_pk_add_f32 v[10:11], v[10:11], v[70:71]
	v_pk_add_f32 v[8:9], v[8:9], v[76:77]
	v_pk_add_f32 v[6:7], v[6:7], v[74:75]
	v_pk_add_f32 v[4:5], v[4:5], v[68:69]
	v_pk_add_f32 v[2:3], v[2:3], v[66:67]
	global_store_dwordx4 v[94:95], v[62:65], off
	global_store_dwordx4 v[94:95], v[58:61], off offset:16
	global_store_dwordx4 v[50:51], v[46:49], off
	global_store_dwordx4 v[50:51], v[42:45], off offset:16
	global_store_dwordx4 v[34:35], v[30:33], off
	global_store_dwordx4 v[34:35], v[26:29], off offset:16
	global_store_dwordx4 v[18:19], v[14:17], off
	global_store_dwordx4 v[18:19], v[10:13], off offset:16
	global_store_dwordx4 v[18:19], v[6:9], off offset:512
	global_store_dwordx4 v[18:19], v[2:5], off offset:528
	s_cbranch_vccz .LBB0_1082
	s_waitcnt vmcnt(0)
	s_cmpk_gt_u32 s28, 0xff
	s_cbranch_scc1 .LBB0_1093
	s_barrier
